# SP2+first-iteration wait skip in P1,P7,P13,P14; P1/P7 half-1 bias hoist with counted waits
# baseline (speedup 1.0000x reference)
.LBB0_184:
	s_add_u32 s28, s12, 0x4e00000
	s_addc_u32 s29, s13, 0
	s_add_u32 s33, s12, 0x2100000
	s_addc_u32 s35, s13, 0
	s_sext_i32_i8 s20, s8
	s_lshl_b32 s8, s8, 9
	s_and_b32 s8, s8, 0x600
	s_add_u32 s10, s28, s10
	s_addc_u32 s11, s29, s11
	s_add_u32 s60, s10, s8
	s_addc_u32 s61, s11, 0
	s_lshl_b32 s10, s20, 8
	s_ashr_i32 s11, s10, 31
	s_lshl_b64 s[10:11], s[10:11], 2
	s_add_u32 s58, s33, s10
	s_mov_b64 s[38:39], 0x80
	s_addc_u32 s59, s35, s11
	v_lshl_add_u64 v[10:11], v[2:3], 0, s[38:39]
	s_add_i32 m0, s7, 0x18000
	s_mov_b64 s[42:43], 0x20080
	s_waitcnt vmcnt(2)
	s_mov_b32 s98, 0
	s_barrier
	global_load_lds_dwordx4 v[10:11], off
	v_lshl_add_u64 v[10:11], v[2:3], 0, s[42:43]
	s_add_i32 m0, s7, 0x1a000
	s_add_i32 s37, s7, 0x8000
	global_load_lds_dwordx4 v[10:11], off
	v_lshl_add_u64 v[10:11], v[4:5], 0, s[38:39]
	s_mov_b32 m0, s37
	s_add_i32 s40, s7, 0xa000
	global_load_lds_dwordx4 v[10:11], off
	v_lshl_add_u64 v[4:5], v[4:5], 0, s[42:43]
	s_mov_b32 m0, s40
	s_mov_b64 s[44:45], 0x40080
	global_load_lds_dwordx4 v[4:5], off
	v_lshl_add_u64 v[4:5], v[2:3], 0, s[44:45]
	s_add_i32 m0, s7, 0x1c000
	s_mov_b64 s[46:47], 0x60080
	global_load_lds_dwordx4 v[4:5], off
	v_lshl_add_u64 v[2:3], v[2:3], 0, s[46:47]
	s_add_i32 m0, s7, 0x1e000
	v_bfe_u32 v153, v6, 4, 2
	global_load_lds_dwordx4 v[2:3], off
	s_lshl_b32 s1, s1, 5
	v_and_b32_e32 v152, 15, v6
	v_lshlrev_b32_e32 v2, 4, v153
	v_lshlrev_b32_e32 v3, 2, v6
	s_and_b32 s70, s1, 0x60
	v_lshl_or_b32 v2, v152, 6, v2
	s_lshl_b32 s8, s9, 13
	v_and_b32_e32 v3, 32, v3
	s_lshl_b32 s1, s70, 7
	v_bitop3_b32 v4, v2, s8, v3 bitop3:0xde
	v_bitop3_b32 v154, v2, s1, v3 bitop3:0xde
	v_lshlrev_b32_e32 v2, 14, v8
	s_lshl_b32 s41, s9, 6
	v_and_b32_e32 v2, 0xffff8000, v2
	s_waitcnt vmcnt(6)
	s_cmpk_lt_u32 s0, 0x100
	v_lshl_add_u32 v2, v7, 11, v2
	v_and_b32_e32 v3, 1, v8
	s_cselect_b64 s[48:49], -1, 0
	v_lshl_or_b32 v2, v3, 6, v2
	s_add_i32 s75, 0, 0x10000
	s_add_i32 s76, 0, 0x14000
	s_mov_b32 s71, 0x18000
	s_mov_b32 s72, 0x8000
	s_ashr_i32 s73, s90, 31
	s_mov_b32 s74, s90
	v_lshl_add_u32 v142, v9, 1, v2
	v_mov_b32_e32 v143, v139
	v_mov_b64_e32 v[144:145], 0x100
	v_mov_b64_e32 v[146:147], 0xff
	v_add_u32_e32 v155, s75, v154
	v_add_u32_e32 v156, 0, v4
	v_add_u32_e32 v157, s76, v154
	s_lshl_b32 s20, s70, 1
	s_mov_b32 s77, 0x40000
	s_mov_b32 s78, 0x48000
	s_mov_b32 s79, 0x50000
	s_mov_b32 s80, s21
	s_barrier
	s_branch .LBB0_187

.LBB0_190:
	ds_read_b128 v[130:133], v155
	ds_read_b128 v[134:137], v155 offset:1024
	ds_read_b128 v[148:151], v155 offset:2048
	ds_read_b128 v[158:161], v155 offset:3072
	ds_read_b128 v[194:197], v157
	ds_read_b128 v[198:201], v157 offset:1024
	ds_read_b128 v[202:205], v157 offset:2048
	ds_read_b128 v[206:209], v157 offset:3072
	s_add_u32 s0, s64, 0xfffc0080
	s_addc_u32 s1, s65, -1
	s_cmp_eq_u32 s68, 12
	s_cselect_b32 s1, s11, s1
	s_cselect_b32 s0, s10, s0
	s_cselect_b32 s31, s63, s67
	s_cselect_b32 s30, s62, s66
	v_lshl_add_u64 v[252:253], s[64:65], 0, v[142:143]
	s_add_i32 m0, s7, 0xc000
	ds_read_b128 v[162:165], v156
	ds_read_b128 v[166:169], v156 offset:1024
	ds_read_b128 v[170:173], v156 offset:2048
	ds_read_b128 v[174:177], v156 offset:3072
	ds_read_b128 v[178:181], v156 offset:4096
	ds_read_b128 v[182:185], v156 offset:5120
	ds_read_b128 v[186:189], v156 offset:6144
	ds_read_b128 v[190:193], v156 offset:7168
	global_load_lds_dwordx4 v[252:253], off
	v_lshl_add_u64 v[252:253], v[252:253], 0, s[14:15]
	s_add_i32 m0, s7, 0xe000
	s_nop 0
	global_load_lds_dwordx4 v[252:253], off
	s_cmp_lg_u32 s98, 0
	s_cbranch_scc1 .Lsk1_p1
	s_waitcnt vmcnt(8)
.Lsk1_p1:
	s_waitcnt lgkmcnt(0)
	s_barrier
	s_setprio 1
	v_mfma_f32_16x16x32_bf16 v[126:129], v[130:133], v[162:165], v[126:129]
	v_mfma_f32_16x16x32_bf16 v[122:125], v[148:151], v[162:165], v[122:125]
	v_mfma_f32_16x16x32_bf16 v[118:121], v[130:133], v[170:173], v[118:121]
	v_mfma_f32_16x16x32_bf16 v[114:117], v[148:151], v[170:173], v[114:117]
	v_mfma_f32_16x16x32_bf16 v[110:113], v[130:133], v[178:181], v[110:113]
	v_mfma_f32_16x16x32_bf16 v[106:109], v[148:151], v[178:181], v[106:109]
	v_mfma_f32_16x16x32_bf16 v[102:105], v[130:133], v[186:189], v[102:105]
	v_mfma_f32_16x16x32_bf16 v[98:101], v[148:151], v[186:189], v[98:101]
	v_mfma_f32_16x16x32_bf16 v[126:129], v[134:137], v[166:169], v[126:129]
	v_mfma_f32_16x16x32_bf16 v[122:125], v[158:161], v[166:169], v[122:125]
	v_mfma_f32_16x16x32_bf16 v[118:121], v[134:137], v[174:177], v[118:121]
	v_mfma_f32_16x16x32_bf16 v[114:117], v[158:161], v[174:177], v[114:117]
	v_mfma_f32_16x16x32_bf16 v[110:113], v[134:137], v[182:185], v[110:113]
	v_mfma_f32_16x16x32_bf16 v[106:109], v[158:161], v[182:185], v[106:109]
	v_mfma_f32_16x16x32_bf16 v[102:105], v[134:137], v[190:193], v[102:105]
	v_mfma_f32_16x16x32_bf16 v[98:101], v[158:161], v[190:193], v[98:101]
	v_mfma_f32_16x16x32_bf16 v[62:65], v[194:197], v[162:165], v[62:65]
	v_mfma_f32_16x16x32_bf16 v[58:61], v[202:205], v[162:165], v[58:61]
	v_mfma_f32_16x16x32_bf16 v[54:57], v[194:197], v[170:173], v[54:57]
	v_mfma_f32_16x16x32_bf16 v[50:53], v[202:205], v[170:173], v[50:53]
	v_mfma_f32_16x16x32_bf16 v[46:49], v[194:197], v[178:181], v[46:49]
	v_mfma_f32_16x16x32_bf16 v[42:45], v[202:205], v[178:181], v[42:45]
	v_mfma_f32_16x16x32_bf16 v[38:41], v[194:197], v[186:189], v[38:41]
	v_mfma_f32_16x16x32_bf16 v[34:37], v[202:205], v[186:189], v[34:37]
	v_mfma_f32_16x16x32_bf16 v[62:65], v[198:201], v[166:169], v[62:65]
	v_mfma_f32_16x16x32_bf16 v[58:61], v[206:209], v[166:169], v[58:61]
	v_mfma_f32_16x16x32_bf16 v[54:57], v[198:201], v[174:177], v[54:57]
	v_mfma_f32_16x16x32_bf16 v[50:53], v[206:209], v[174:177], v[50:53]
	v_mfma_f32_16x16x32_bf16 v[46:49], v[198:201], v[182:185], v[46:49]
	v_mfma_f32_16x16x32_bf16 v[42:45], v[206:209], v[182:185], v[42:45]
	v_mfma_f32_16x16x32_bf16 v[38:41], v[198:201], v[190:193], v[38:41]
	v_mfma_f32_16x16x32_bf16 v[34:37], v[206:209], v[190:193], v[34:37]
	s_setprio 0
	s_barrier
	ds_read_b128 v[162:165], v156 offset:16384
	ds_read_b128 v[166:169], v156 offset:17408
	ds_read_b128 v[170:173], v156 offset:18432
	ds_read_b128 v[174:177], v156 offset:19456
	ds_read_b128 v[178:181], v156 offset:20480
	ds_read_b128 v[182:185], v156 offset:21504
	ds_read_b128 v[186:189], v156 offset:22528
	ds_read_b128 v[190:193], v156 offset:23552
	v_lshl_add_u64 v[212:213], s[0:1], 0, v[140:141]
	v_lshl_add_u64 v[210:211], s[30:31], 0, v[138:139]
	s_add_i32 s30, s75, s5
	s_mov_b32 m0, s30
	s_nop 0
	global_load_lds_dwordx4 v[210:211], off
	v_lshl_add_u64 v[214:215], v[210:211], 0, s[14:15]
	s_add_i32 m0, s30, 0x2000
	s_nop 0
	global_load_lds_dwordx4 v[214:215], off
	s_add_i32 s0, s76, s5
	v_lshl_add_u64 v[250:251], v[210:211], 0, s[16:17]
	s_mov_b32 m0, s0
	s_nop 0
	global_load_lds_dwordx4 v[250:251], off
	v_lshl_add_u64 v[250:251], v[210:211], 0, s[18:19]
	s_add_i32 m0, s0, 0x2000
	s_nop 0
	global_load_lds_dwordx4 v[250:251], off
	s_mov_b32 m0, s7
	s_nop 0
	global_load_lds_dwordx4 v[212:213], off
	v_lshl_add_u64 v[214:215], v[212:213], 0, s[14:15]
	s_mov_b32 m0, s24
	s_nop 0
	global_load_lds_dwordx4 v[214:215], off
	s_cmp_lg_u32 s98, 0
	s_cbranch_scc1 .Lsk2_p1
	s_waitcnt vmcnt(8)
.Lsk2_p1:
	s_mov_b32 s98, 0
	s_waitcnt lgkmcnt(0)
	s_barrier
	s_setprio 1
	v_mfma_f32_16x16x32_bf16 v[94:97], v[130:133], v[162:165], v[94:97]
	v_mfma_f32_16x16x32_bf16 v[90:93], v[148:151], v[162:165], v[90:93]
	v_mfma_f32_16x16x32_bf16 v[86:89], v[130:133], v[170:173], v[86:89]
	v_mfma_f32_16x16x32_bf16 v[82:85], v[148:151], v[170:173], v[82:85]
	v_mfma_f32_16x16x32_bf16 v[78:81], v[130:133], v[178:181], v[78:81]
	v_mfma_f32_16x16x32_bf16 v[74:77], v[148:151], v[178:181], v[74:77]
	v_mfma_f32_16x16x32_bf16 v[70:73], v[130:133], v[186:189], v[70:73]
	v_mfma_f32_16x16x32_bf16 v[66:69], v[148:151], v[186:189], v[66:69]
	v_mfma_f32_16x16x32_bf16 v[94:97], v[134:137], v[166:169], v[94:97]
	v_mfma_f32_16x16x32_bf16 v[90:93], v[158:161], v[166:169], v[90:93]
	v_mfma_f32_16x16x32_bf16 v[86:89], v[134:137], v[174:177], v[86:89]
	v_mfma_f32_16x16x32_bf16 v[82:85], v[158:161], v[174:177], v[82:85]
	v_mfma_f32_16x16x32_bf16 v[78:81], v[134:137], v[182:185], v[78:81]
	v_mfma_f32_16x16x32_bf16 v[74:77], v[158:161], v[182:185], v[74:77]
	v_mfma_f32_16x16x32_bf16 v[70:73], v[134:137], v[190:193], v[70:73]
	v_mfma_f32_16x16x32_bf16 v[66:69], v[158:161], v[190:193], v[66:69]
	v_mfma_f32_16x16x32_bf16 v[30:33], v[194:197], v[162:165], v[30:33]
	v_mfma_f32_16x16x32_bf16 v[26:29], v[202:205], v[162:165], v[26:29]
	v_mfma_f32_16x16x32_bf16 v[22:25], v[194:197], v[170:173], v[22:25]
	v_mfma_f32_16x16x32_bf16 v[18:21], v[202:205], v[170:173], v[18:21]
	v_mfma_f32_16x16x32_bf16 v[14:17], v[194:197], v[178:181], v[14:17]
	v_mfma_f32_16x16x32_bf16 v[10:13], v[202:205], v[178:181], v[10:13]
	v_mfma_f32_16x16x32_bf16 v[6:9], v[194:197], v[186:189], v[6:9]
	v_mfma_f32_16x16x32_bf16 v[2:5], v[202:205], v[186:189], v[2:5]
	v_mfma_f32_16x16x32_bf16 v[30:33], v[198:201], v[166:169], v[30:33]
	v_mfma_f32_16x16x32_bf16 v[26:29], v[206:209], v[166:169], v[26:29]
	v_mfma_f32_16x16x32_bf16 v[22:25], v[198:201], v[174:177], v[22:25]
	v_mfma_f32_16x16x32_bf16 v[18:21], v[206:209], v[174:177], v[18:21]
	v_mfma_f32_16x16x32_bf16 v[14:17], v[198:201], v[182:185], v[14:17]
	v_mfma_f32_16x16x32_bf16 v[10:13], v[206:209], v[182:185], v[10:13]
	v_mfma_f32_16x16x32_bf16 v[6:9], v[198:201], v[190:193], v[6:9]
	v_mfma_f32_16x16x32_bf16 v[2:5], v[206:209], v[190:193], v[2:5]
	s_setprio 0
	s_add_i32 s0, 0, 0x18000
	v_add_u32_e32 v158, s0, v154
	s_barrier
	s_add_i32 s1, 0, 0x1c000
	v_add_u32_e32 v206, s1, v154
	ds_read_b128 v[130:133], v158
	ds_read_b128 v[134:137], v158 offset:1024
	ds_read_b128 v[148:151], v158 offset:2048
	ds_read_b128 v[158:161], v158 offset:3072
	ds_read_b128 v[194:197], v206
	ds_read_b128 v[198:201], v206 offset:1024
	ds_read_b128 v[202:205], v206 offset:2048
	ds_read_b128 v[206:209], v206 offset:3072
	s_mov_b32 m0, s25
	v_lshl_add_u64 v[252:253], v[212:213], 0, s[16:17]
	ds_read_b128 v[162:165], v156 offset:32768
	ds_read_b128 v[166:169], v156 offset:33792
	ds_read_b128 v[170:173], v156 offset:34816
	ds_read_b128 v[174:177], v156 offset:35840
	ds_read_b128 v[178:181], v156 offset:36864
	ds_read_b128 v[182:185], v156 offset:37888
	ds_read_b128 v[186:189], v156 offset:38912
	ds_read_b128 v[190:193], v156 offset:39936
	global_load_lds_dwordx4 v[252:253], off
	v_lshl_add_u64 v[252:253], v[212:213], 0, s[18:19]
	s_mov_b32 m0, s26
	s_nop 0
	global_load_lds_dwordx4 v[252:253], off
	s_waitcnt vmcnt(8)
	s_waitcnt lgkmcnt(0)
	s_barrier
	s_setprio 1
	v_mfma_f32_16x16x32_bf16 v[126:129], v[130:133], v[162:165], v[126:129]
	v_mfma_f32_16x16x32_bf16 v[122:125], v[148:151], v[162:165], v[122:125]
	v_mfma_f32_16x16x32_bf16 v[118:121], v[130:133], v[170:173], v[118:121]
	v_mfma_f32_16x16x32_bf16 v[114:117], v[148:151], v[170:173], v[114:117]
	v_mfma_f32_16x16x32_bf16 v[110:113], v[130:133], v[178:181], v[110:113]
	v_mfma_f32_16x16x32_bf16 v[106:109], v[148:151], v[178:181], v[106:109]
	v_mfma_f32_16x16x32_bf16 v[102:105], v[130:133], v[186:189], v[102:105]
	v_mfma_f32_16x16x32_bf16 v[98:101], v[148:151], v[186:189], v[98:101]
	v_mfma_f32_16x16x32_bf16 v[126:129], v[134:137], v[166:169], v[126:129]
	v_mfma_f32_16x16x32_bf16 v[122:125], v[158:161], v[166:169], v[122:125]
	v_mfma_f32_16x16x32_bf16 v[118:121], v[134:137], v[174:177], v[118:121]
	v_mfma_f32_16x16x32_bf16 v[114:117], v[158:161], v[174:177], v[114:117]
	v_mfma_f32_16x16x32_bf16 v[110:113], v[134:137], v[182:185], v[110:113]
	v_mfma_f32_16x16x32_bf16 v[106:109], v[158:161], v[182:185], v[106:109]
	v_mfma_f32_16x16x32_bf16 v[102:105], v[134:137], v[190:193], v[102:105]
	v_mfma_f32_16x16x32_bf16 v[98:101], v[158:161], v[190:193], v[98:101]
	v_mfma_f32_16x16x32_bf16 v[62:65], v[194:197], v[162:165], v[62:65]
	v_mfma_f32_16x16x32_bf16 v[58:61], v[202:205], v[162:165], v[58:61]
	v_mfma_f32_16x16x32_bf16 v[54:57], v[194:197], v[170:173], v[54:57]
	v_mfma_f32_16x16x32_bf16 v[50:53], v[202:205], v[170:173], v[50:53]
	v_mfma_f32_16x16x32_bf16 v[46:49], v[194:197], v[178:181], v[46:49]
	v_mfma_f32_16x16x32_bf16 v[42:45], v[202:205], v[178:181], v[42:45]
	v_mfma_f32_16x16x32_bf16 v[38:41], v[194:197], v[186:189], v[38:41]
	v_mfma_f32_16x16x32_bf16 v[34:37], v[202:205], v[186:189], v[34:37]
	v_mfma_f32_16x16x32_bf16 v[62:65], v[198:201], v[166:169], v[62:65]
	v_mfma_f32_16x16x32_bf16 v[58:61], v[206:209], v[166:169], v[58:61]
	v_mfma_f32_16x16x32_bf16 v[54:57], v[198:201], v[174:177], v[54:57]
	v_mfma_f32_16x16x32_bf16 v[50:53], v[206:209], v[174:177], v[50:53]
	v_mfma_f32_16x16x32_bf16 v[46:49], v[198:201], v[182:185], v[46:49]
	v_mfma_f32_16x16x32_bf16 v[42:45], v[206:209], v[182:185], v[42:45]
	v_mfma_f32_16x16x32_bf16 v[38:41], v[198:201], v[190:193], v[38:41]
	v_mfma_f32_16x16x32_bf16 v[34:37], v[206:209], v[190:193], v[34:37]
	s_setprio 0
	s_barrier
	ds_read_b128 v[162:165], v156 offset:49152
	ds_read_b128 v[166:169], v156 offset:50176
	ds_read_b128 v[170:173], v156 offset:51200
	ds_read_b128 v[174:177], v156 offset:52224
	ds_read_b128 v[178:181], v156 offset:53248
	ds_read_b128 v[182:185], v156 offset:54272
	ds_read_b128 v[186:189], v156 offset:55296
	ds_read_b128 v[190:193], v156 offset:56320
	s_add_i32 s0, s0, s5
	v_lshl_add_u64 v[214:215], v[210:211], 0, s[38:39]
	s_mov_b32 m0, s0
	s_nop 0
	global_load_lds_dwordx4 v[214:215], off
	v_lshl_add_u64 v[214:215], v[210:211], 0, s[42:43]
	s_add_i32 m0, s0, 0x2000
	s_nop 0
	global_load_lds_dwordx4 v[214:215], off
	s_add_i32 s0, s1, s5
	v_lshl_add_u64 v[250:251], v[210:211], 0, s[44:45]
	s_mov_b32 m0, s0
	s_nop 0
	global_load_lds_dwordx4 v[250:251], off
	v_lshl_add_u64 v[250:251], v[210:211], 0, s[46:47]
	s_add_i32 m0, s0, 0x2000
	s_nop 0
	global_load_lds_dwordx4 v[250:251], off
	s_mov_b32 m0, s37
	v_lshl_add_u64 v[214:215], v[212:213], 0, s[38:39]
	global_load_lds_dwordx4 v[214:215], off
	v_lshl_add_u64 v[212:213], v[212:213], 0, s[42:43]
	s_mov_b32 m0, s40
	s_nop 0
	global_load_lds_dwordx4 v[212:213], off
	s_waitcnt vmcnt(8)
	s_waitcnt lgkmcnt(0)
	s_barrier
	s_setprio 1
	v_mfma_f32_16x16x32_bf16 v[94:97], v[130:133], v[162:165], v[94:97]
	v_mfma_f32_16x16x32_bf16 v[90:93], v[148:151], v[162:165], v[90:93]
	v_mfma_f32_16x16x32_bf16 v[86:89], v[130:133], v[170:173], v[86:89]
	v_mfma_f32_16x16x32_bf16 v[82:85], v[148:151], v[170:173], v[82:85]
	v_mfma_f32_16x16x32_bf16 v[78:81], v[130:133], v[178:181], v[78:81]
	v_mfma_f32_16x16x32_bf16 v[74:77], v[148:151], v[178:181], v[74:77]
	v_mfma_f32_16x16x32_bf16 v[70:73], v[130:133], v[186:189], v[70:73]
	v_mfma_f32_16x16x32_bf16 v[66:69], v[148:151], v[186:189], v[66:69]
	v_mfma_f32_16x16x32_bf16 v[94:97], v[134:137], v[166:169], v[94:97]
	v_mfma_f32_16x16x32_bf16 v[90:93], v[158:161], v[166:169], v[90:93]
	v_mfma_f32_16x16x32_bf16 v[86:89], v[134:137], v[174:177], v[86:89]
	v_mfma_f32_16x16x32_bf16 v[82:85], v[158:161], v[174:177], v[82:85]
	v_mfma_f32_16x16x32_bf16 v[78:81], v[134:137], v[182:185], v[78:81]
	v_mfma_f32_16x16x32_bf16 v[74:77], v[158:161], v[182:185], v[74:77]
	v_mfma_f32_16x16x32_bf16 v[70:73], v[134:137], v[190:193], v[70:73]
	v_mfma_f32_16x16x32_bf16 v[66:69], v[158:161], v[190:193], v[66:69]
	v_mfma_f32_16x16x32_bf16 v[30:33], v[194:197], v[162:165], v[30:33]
	v_mfma_f32_16x16x32_bf16 v[26:29], v[202:205], v[162:165], v[26:29]
	v_mfma_f32_16x16x32_bf16 v[22:25], v[194:197], v[170:173], v[22:25]
	v_mfma_f32_16x16x32_bf16 v[18:21], v[202:205], v[170:173], v[18:21]
	v_mfma_f32_16x16x32_bf16 v[14:17], v[194:197], v[178:181], v[14:17]
	v_mfma_f32_16x16x32_bf16 v[10:13], v[202:205], v[178:181], v[10:13]
	v_mfma_f32_16x16x32_bf16 v[6:9], v[194:197], v[186:189], v[6:9]
	v_mfma_f32_16x16x32_bf16 v[2:5], v[202:205], v[186:189], v[2:5]
	v_mfma_f32_16x16x32_bf16 v[30:33], v[198:201], v[166:169], v[30:33]
	v_mfma_f32_16x16x32_bf16 v[26:29], v[206:209], v[166:169], v[26:29]
	v_mfma_f32_16x16x32_bf16 v[22:25], v[198:201], v[174:177], v[22:25]
	v_mfma_f32_16x16x32_bf16 v[18:21], v[206:209], v[174:177], v[18:21]
	v_mfma_f32_16x16x32_bf16 v[14:17], v[198:201], v[182:185], v[14:17]
	v_mfma_f32_16x16x32_bf16 v[10:13], v[206:209], v[182:185], v[10:13]
	v_mfma_f32_16x16x32_bf16 v[6:9], v[198:201], v[190:193], v[6:9]
	v_mfma_f32_16x16x32_bf16 v[2:5], v[206:209], v[190:193], v[2:5]
	s_setprio 0
	s_add_i32 s68, s68, 2
	s_add_u32 s66, s66, 0x100
	s_addc_u32 s67, s67, 0
	s_add_u32 s64, s64, 0x100
	s_addc_u32 s65, s65, 0
	s_cmp_gt_u32 s68, 13
	s_barrier
	s_cbranch_scc0 .LBB0_190
	s_mov_b32 s98, 1
	s_and_b64 vcc, exec, s[48:49]
	s_cbranch_vccz .LBB0_193
	s_barrier

.LBB0_1043:
	s_add_u32 s27, s10, 0x2e00000
	s_addc_u32 s28, s11, 0
	s_add_u32 s29, s10, 0x4e00000
	s_addc_u32 s33, s11, 0
	s_add_u32 s35, s10, 0x2101000
	s_addc_u32 s39, s11, 0
	s_and_b32 s10, s12, 0xff
	s_cmp_lt_u32 s10, 4
	s_sext_i32_i8 s11, s12
	s_cselect_b32 s10, s28, s33
	s_cselect_b32 s30, s27, s29
	s_lshl_b32 s12, s12, 9
	s_and_b32 s12, s12, 0x600
	s_add_u32 s30, s30, s42
	s_addc_u32 s10, s10, s43
	s_add_u32 s62, s30, s12
	s_addc_u32 s63, s10, 0
	s_lshl_b32 s10, s11, 8
	s_ashr_i32 s11, s10, 31
	s_lshl_b64 s[10:11], s[10:11], 2
	s_add_u32 s60, s35, s10
	s_mov_b64 s[42:43], 0x80
	s_addc_u32 s61, s39, s11
	v_lshl_add_u64 v[10:11], v[2:3], 0, s[42:43]
	s_add_i32 m0, s9, 0x18000
	s_mov_b64 s[44:45], 0x20080
	s_waitcnt vmcnt(2)
	s_mov_b32 s98, 0
	s_barrier
	global_load_lds_dwordx4 v[10:11], off
	v_lshl_add_u64 v[10:11], v[2:3], 0, s[44:45]
	s_add_i32 m0, s9, 0x1a000
	s_add_i32 s72, s9, 0x8000
	global_load_lds_dwordx4 v[10:11], off
	v_lshl_add_u64 v[10:11], v[4:5], 0, s[42:43]
	s_mov_b32 m0, s72
	s_add_i32 s73, s9, 0xa000
	global_load_lds_dwordx4 v[10:11], off
	v_lshl_add_u64 v[4:5], v[4:5], 0, s[44:45]
	s_mov_b32 m0, s73
	s_mov_b64 s[46:47], 0x40080
	global_load_lds_dwordx4 v[4:5], off
	v_lshl_add_u64 v[4:5], v[2:3], 0, s[46:47]
	s_add_i32 m0, s9, 0x1c000
	s_mov_b64 s[48:49], 0x60080
	global_load_lds_dwordx4 v[4:5], off
	v_lshl_add_u64 v[2:3], v[2:3], 0, s[48:49]
	s_add_i32 m0, s9, 0x1e000
	v_bfe_u32 v153, v6, 4, 2
	global_load_lds_dwordx4 v[2:3], off
	s_lshl_b32 s1, s1, 5
	v_and_b32_e32 v152, 15, v6
	v_lshlrev_b32_e32 v2, 4, v153
	v_lshlrev_b32_e32 v3, 2, v6
	s_and_b32 s75, s1, 0x60
	v_lshl_or_b32 v2, v152, 6, v2
	s_lshl_b32 s10, s13, 13
	v_and_b32_e32 v3, 32, v3
	s_lshl_b32 s1, s75, 7
	v_bitop3_b32 v4, v2, s10, v3 bitop3:0xde
	v_bitop3_b32 v154, v2, s1, v3 bitop3:0xde
	v_lshlrev_b32_e32 v2, 14, v8
	s_lshl_b32 s74, s13, 6
	v_and_b32_e32 v2, 0xffff8000, v2
	s_waitcnt vmcnt(6)
	s_cmpk_lt_u32 s0, 0x100
	v_lshl_add_u32 v2, v7, 11, v2
	v_and_b32_e32 v3, 1, v8
	s_cselect_b64 s[50:51], -1, 0
	v_lshl_or_b32 v2, v3, 6, v2
	s_add_i32 s78, 0, 0x10000
	s_add_i32 s79, 0, 0x14000
	s_ashr_i32 s76, s90, 31
	s_mov_b32 s77, s90
	v_lshl_add_u32 v142, v9, 1, v2
	v_mov_b32_e32 v143, v139
	v_mov_b64_e32 v[144:145], 0x200
	v_mov_b64_e32 v[146:147], 0x1ff
	v_add_u32_e32 v155, s78, v154
	v_add_u32_e32 v156, 0, v4
	v_add_u32_e32 v157, s79, v154
	s_lshl_b32 s40, s75, 1
	s_mov_b32 s80, 0x48000
	s_mov_b32 s81, 0x50000
	s_mov_b32 s82, s41
	s_barrier
	s_branch .LBB0_1046

.LBB0_1049:
	ds_read_b128 v[130:133], v155
	ds_read_b128 v[134:137], v155 offset:1024
	ds_read_b128 v[148:151], v155 offset:2048
	ds_read_b128 v[158:161], v155 offset:3072
	ds_read_b128 v[194:197], v157
	ds_read_b128 v[198:201], v157 offset:1024
	ds_read_b128 v[202:205], v157 offset:2048
	ds_read_b128 v[206:209], v157 offset:3072
	s_add_u32 s0, s66, 0xfffc0080
	s_addc_u32 s1, s67, -1
	s_cmp_eq_u32 s69, 12
	s_cselect_b32 s1, s13, s1
	s_cselect_b32 s0, s12, s0
	s_cselect_b32 s31, s65, s68
	s_cselect_b32 s30, s64, s38
	v_lshl_add_u64 v[252:253], s[66:67], 0, v[142:143]
	s_add_i32 m0, s9, 0xc000
	ds_read_b128 v[162:165], v156
	ds_read_b128 v[166:169], v156 offset:1024
	ds_read_b128 v[170:173], v156 offset:2048
	ds_read_b128 v[174:177], v156 offset:3072
	ds_read_b128 v[178:181], v156 offset:4096
	ds_read_b128 v[182:185], v156 offset:5120
	ds_read_b128 v[186:189], v156 offset:6144
	ds_read_b128 v[190:193], v156 offset:7168
	global_load_lds_dwordx4 v[252:253], off
	v_lshl_add_u64 v[252:253], v[252:253], 0, s[14:15]
	s_add_i32 m0, s9, 0xe000
	s_nop 0
	global_load_lds_dwordx4 v[252:253], off
	s_cmp_lg_u32 s98, 0
	s_cbranch_scc1 .Lsk1_p7
	s_waitcnt vmcnt(8)
.Lsk1_p7:
	s_waitcnt lgkmcnt(0)
	s_barrier
	s_setprio 1
	v_mfma_f32_16x16x32_bf16 v[126:129], v[130:133], v[162:165], v[126:129]
	v_mfma_f32_16x16x32_bf16 v[122:125], v[148:151], v[162:165], v[122:125]
	v_mfma_f32_16x16x32_bf16 v[118:121], v[130:133], v[170:173], v[118:121]
	v_mfma_f32_16x16x32_bf16 v[114:117], v[148:151], v[170:173], v[114:117]
	v_mfma_f32_16x16x32_bf16 v[110:113], v[130:133], v[178:181], v[110:113]
	v_mfma_f32_16x16x32_bf16 v[106:109], v[148:151], v[178:181], v[106:109]
	v_mfma_f32_16x16x32_bf16 v[102:105], v[130:133], v[186:189], v[102:105]
	v_mfma_f32_16x16x32_bf16 v[98:101], v[148:151], v[186:189], v[98:101]
	v_mfma_f32_16x16x32_bf16 v[126:129], v[134:137], v[166:169], v[126:129]
	v_mfma_f32_16x16x32_bf16 v[122:125], v[158:161], v[166:169], v[122:125]
	v_mfma_f32_16x16x32_bf16 v[118:121], v[134:137], v[174:177], v[118:121]
	v_mfma_f32_16x16x32_bf16 v[114:117], v[158:161], v[174:177], v[114:117]
	v_mfma_f32_16x16x32_bf16 v[110:113], v[134:137], v[182:185], v[110:113]
	v_mfma_f32_16x16x32_bf16 v[106:109], v[158:161], v[182:185], v[106:109]
	v_mfma_f32_16x16x32_bf16 v[102:105], v[134:137], v[190:193], v[102:105]
	v_mfma_f32_16x16x32_bf16 v[98:101], v[158:161], v[190:193], v[98:101]
	v_mfma_f32_16x16x32_bf16 v[62:65], v[194:197], v[162:165], v[62:65]
	v_mfma_f32_16x16x32_bf16 v[58:61], v[202:205], v[162:165], v[58:61]
	v_mfma_f32_16x16x32_bf16 v[54:57], v[194:197], v[170:173], v[54:57]
	v_mfma_f32_16x16x32_bf16 v[50:53], v[202:205], v[170:173], v[50:53]
	v_mfma_f32_16x16x32_bf16 v[46:49], v[194:197], v[178:181], v[46:49]
	v_mfma_f32_16x16x32_bf16 v[42:45], v[202:205], v[178:181], v[42:45]
	v_mfma_f32_16x16x32_bf16 v[38:41], v[194:197], v[186:189], v[38:41]
	v_mfma_f32_16x16x32_bf16 v[34:37], v[202:205], v[186:189], v[34:37]
	v_mfma_f32_16x16x32_bf16 v[62:65], v[198:201], v[166:169], v[62:65]
	v_mfma_f32_16x16x32_bf16 v[58:61], v[206:209], v[166:169], v[58:61]
	v_mfma_f32_16x16x32_bf16 v[54:57], v[198:201], v[174:177], v[54:57]
	v_mfma_f32_16x16x32_bf16 v[50:53], v[206:209], v[174:177], v[50:53]
	v_mfma_f32_16x16x32_bf16 v[46:49], v[198:201], v[182:185], v[46:49]
	v_mfma_f32_16x16x32_bf16 v[42:45], v[206:209], v[182:185], v[42:45]
	v_mfma_f32_16x16x32_bf16 v[38:41], v[198:201], v[190:193], v[38:41]
	v_mfma_f32_16x16x32_bf16 v[34:37], v[206:209], v[190:193], v[34:37]
	s_setprio 0
	s_barrier
	ds_read_b128 v[162:165], v156 offset:16384
	ds_read_b128 v[166:169], v156 offset:17408
	ds_read_b128 v[170:173], v156 offset:18432
	ds_read_b128 v[174:177], v156 offset:19456
	ds_read_b128 v[178:181], v156 offset:20480
	ds_read_b128 v[182:185], v156 offset:21504
	ds_read_b128 v[186:189], v156 offset:22528
	ds_read_b128 v[190:193], v156 offset:23552
	v_lshl_add_u64 v[212:213], s[0:1], 0, v[140:141]
	v_lshl_add_u64 v[210:211], s[30:31], 0, v[138:139]
	s_add_i32 s30, s78, s7
	s_mov_b32 m0, s30
	s_nop 0
	global_load_lds_dwordx4 v[210:211], off
	v_lshl_add_u64 v[214:215], v[210:211], 0, s[14:15]
	s_add_i32 m0, s30, 0x2000
	s_nop 0
	global_load_lds_dwordx4 v[214:215], off
	s_add_i32 s0, s79, s7
	v_lshl_add_u64 v[250:251], v[210:211], 0, s[18:19]
	s_mov_b32 m0, s0
	s_nop 0
	global_load_lds_dwordx4 v[250:251], off
	v_lshl_add_u64 v[250:251], v[210:211], 0, s[20:21]
	s_add_i32 m0, s0, 0x2000
	s_nop 0
	global_load_lds_dwordx4 v[250:251], off
	s_mov_b32 m0, s9
	s_nop 0
	global_load_lds_dwordx4 v[212:213], off
	v_lshl_add_u64 v[214:215], v[212:213], 0, s[14:15]
	s_mov_b32 m0, s24
	s_nop 0
	global_load_lds_dwordx4 v[214:215], off
	s_cmp_lg_u32 s98, 0
	s_cbranch_scc1 .Lsk2_p7
	s_waitcnt vmcnt(8)
.Lsk2_p7:
	s_mov_b32 s98, 0
	s_waitcnt lgkmcnt(0)
	s_barrier
	s_setprio 1
	v_mfma_f32_16x16x32_bf16 v[94:97], v[130:133], v[162:165], v[94:97]
	v_mfma_f32_16x16x32_bf16 v[90:93], v[148:151], v[162:165], v[90:93]
	v_mfma_f32_16x16x32_bf16 v[86:89], v[130:133], v[170:173], v[86:89]
	v_mfma_f32_16x16x32_bf16 v[82:85], v[148:151], v[170:173], v[82:85]
	v_mfma_f32_16x16x32_bf16 v[78:81], v[130:133], v[178:181], v[78:81]
	v_mfma_f32_16x16x32_bf16 v[74:77], v[148:151], v[178:181], v[74:77]
	v_mfma_f32_16x16x32_bf16 v[70:73], v[130:133], v[186:189], v[70:73]
	v_mfma_f32_16x16x32_bf16 v[66:69], v[148:151], v[186:189], v[66:69]
	v_mfma_f32_16x16x32_bf16 v[94:97], v[134:137], v[166:169], v[94:97]
	v_mfma_f32_16x16x32_bf16 v[90:93], v[158:161], v[166:169], v[90:93]
	v_mfma_f32_16x16x32_bf16 v[86:89], v[134:137], v[174:177], v[86:89]
	v_mfma_f32_16x16x32_bf16 v[82:85], v[158:161], v[174:177], v[82:85]
	v_mfma_f32_16x16x32_bf16 v[78:81], v[134:137], v[182:185], v[78:81]
	v_mfma_f32_16x16x32_bf16 v[74:77], v[158:161], v[182:185], v[74:77]
	v_mfma_f32_16x16x32_bf16 v[70:73], v[134:137], v[190:193], v[70:73]
	v_mfma_f32_16x16x32_bf16 v[66:69], v[158:161], v[190:193], v[66:69]
	v_mfma_f32_16x16x32_bf16 v[30:33], v[194:197], v[162:165], v[30:33]
	v_mfma_f32_16x16x32_bf16 v[26:29], v[202:205], v[162:165], v[26:29]
	v_mfma_f32_16x16x32_bf16 v[22:25], v[194:197], v[170:173], v[22:25]
	v_mfma_f32_16x16x32_bf16 v[18:21], v[202:205], v[170:173], v[18:21]
	v_mfma_f32_16x16x32_bf16 v[14:17], v[194:197], v[178:181], v[14:17]
	v_mfma_f32_16x16x32_bf16 v[10:13], v[202:205], v[178:181], v[10:13]
	v_mfma_f32_16x16x32_bf16 v[6:9], v[194:197], v[186:189], v[6:9]
	v_mfma_f32_16x16x32_bf16 v[2:5], v[202:205], v[186:189], v[2:5]
	v_mfma_f32_16x16x32_bf16 v[30:33], v[198:201], v[166:169], v[30:33]
	v_mfma_f32_16x16x32_bf16 v[26:29], v[206:209], v[166:169], v[26:29]
	v_mfma_f32_16x16x32_bf16 v[22:25], v[198:201], v[174:177], v[22:25]
	v_mfma_f32_16x16x32_bf16 v[18:21], v[206:209], v[174:177], v[18:21]
	v_mfma_f32_16x16x32_bf16 v[14:17], v[198:201], v[182:185], v[14:17]
	v_mfma_f32_16x16x32_bf16 v[10:13], v[206:209], v[182:185], v[10:13]
	v_mfma_f32_16x16x32_bf16 v[6:9], v[198:201], v[190:193], v[6:9]
	v_mfma_f32_16x16x32_bf16 v[2:5], v[206:209], v[190:193], v[2:5]
	s_setprio 0
	s_add_i32 s0, 0, 0x18000
	v_add_u32_e32 v158, s0, v154
	s_barrier
	s_add_i32 s1, 0, 0x1c000
	v_add_u32_e32 v206, s1, v154
	ds_read_b128 v[130:133], v158
	ds_read_b128 v[134:137], v158 offset:1024
	ds_read_b128 v[148:151], v158 offset:2048
	ds_read_b128 v[158:161], v158 offset:3072
	ds_read_b128 v[194:197], v206
	ds_read_b128 v[198:201], v206 offset:1024
	ds_read_b128 v[202:205], v206 offset:2048
	ds_read_b128 v[206:209], v206 offset:3072
	s_mov_b32 m0, s25
	v_lshl_add_u64 v[252:253], v[212:213], 0, s[18:19]
	ds_read_b128 v[162:165], v156 offset:32768
	ds_read_b128 v[166:169], v156 offset:33792
	ds_read_b128 v[170:173], v156 offset:34816
	ds_read_b128 v[174:177], v156 offset:35840
	ds_read_b128 v[178:181], v156 offset:36864
	ds_read_b128 v[182:185], v156 offset:37888
	ds_read_b128 v[186:189], v156 offset:38912
	ds_read_b128 v[190:193], v156 offset:39936
	global_load_lds_dwordx4 v[252:253], off
	v_lshl_add_u64 v[252:253], v[212:213], 0, s[20:21]
	s_mov_b32 m0, s26
	s_nop 0
	global_load_lds_dwordx4 v[252:253], off
	s_waitcnt vmcnt(8)
	s_waitcnt lgkmcnt(0)
	s_barrier
	s_setprio 1
	v_mfma_f32_16x16x32_bf16 v[126:129], v[130:133], v[162:165], v[126:129]
	v_mfma_f32_16x16x32_bf16 v[122:125], v[148:151], v[162:165], v[122:125]
	v_mfma_f32_16x16x32_bf16 v[118:121], v[130:133], v[170:173], v[118:121]
	v_mfma_f32_16x16x32_bf16 v[114:117], v[148:151], v[170:173], v[114:117]
	v_mfma_f32_16x16x32_bf16 v[110:113], v[130:133], v[178:181], v[110:113]
	v_mfma_f32_16x16x32_bf16 v[106:109], v[148:151], v[178:181], v[106:109]
	v_mfma_f32_16x16x32_bf16 v[102:105], v[130:133], v[186:189], v[102:105]
	v_mfma_f32_16x16x32_bf16 v[98:101], v[148:151], v[186:189], v[98:101]
	v_mfma_f32_16x16x32_bf16 v[126:129], v[134:137], v[166:169], v[126:129]
	v_mfma_f32_16x16x32_bf16 v[122:125], v[158:161], v[166:169], v[122:125]
	v_mfma_f32_16x16x32_bf16 v[118:121], v[134:137], v[174:177], v[118:121]
	v_mfma_f32_16x16x32_bf16 v[114:117], v[158:161], v[174:177], v[114:117]
	v_mfma_f32_16x16x32_bf16 v[110:113], v[134:137], v[182:185], v[110:113]
	v_mfma_f32_16x16x32_bf16 v[106:109], v[158:161], v[182:185], v[106:109]
	v_mfma_f32_16x16x32_bf16 v[102:105], v[134:137], v[190:193], v[102:105]
	v_mfma_f32_16x16x32_bf16 v[98:101], v[158:161], v[190:193], v[98:101]
	v_mfma_f32_16x16x32_bf16 v[62:65], v[194:197], v[162:165], v[62:65]
	v_mfma_f32_16x16x32_bf16 v[58:61], v[202:205], v[162:165], v[58:61]
	v_mfma_f32_16x16x32_bf16 v[54:57], v[194:197], v[170:173], v[54:57]
	v_mfma_f32_16x16x32_bf16 v[50:53], v[202:205], v[170:173], v[50:53]
	v_mfma_f32_16x16x32_bf16 v[46:49], v[194:197], v[178:181], v[46:49]
	v_mfma_f32_16x16x32_bf16 v[42:45], v[202:205], v[178:181], v[42:45]
	v_mfma_f32_16x16x32_bf16 v[38:41], v[194:197], v[186:189], v[38:41]
	v_mfma_f32_16x16x32_bf16 v[34:37], v[202:205], v[186:189], v[34:37]
	v_mfma_f32_16x16x32_bf16 v[62:65], v[198:201], v[166:169], v[62:65]
	v_mfma_f32_16x16x32_bf16 v[58:61], v[206:209], v[166:169], v[58:61]
	v_mfma_f32_16x16x32_bf16 v[54:57], v[198:201], v[174:177], v[54:57]
	v_mfma_f32_16x16x32_bf16 v[50:53], v[206:209], v[174:177], v[50:53]
	v_mfma_f32_16x16x32_bf16 v[46:49], v[198:201], v[182:185], v[46:49]
	v_mfma_f32_16x16x32_bf16 v[42:45], v[206:209], v[182:185], v[42:45]
	v_mfma_f32_16x16x32_bf16 v[38:41], v[198:201], v[190:193], v[38:41]
	v_mfma_f32_16x16x32_bf16 v[34:37], v[206:209], v[190:193], v[34:37]
	s_setprio 0
	s_barrier
	ds_read_b128 v[162:165], v156 offset:49152
	ds_read_b128 v[166:169], v156 offset:50176
	ds_read_b128 v[170:173], v156 offset:51200
	ds_read_b128 v[174:177], v156 offset:52224
	ds_read_b128 v[178:181], v156 offset:53248
	ds_read_b128 v[182:185], v156 offset:54272
	ds_read_b128 v[186:189], v156 offset:55296
	ds_read_b128 v[190:193], v156 offset:56320
	s_add_i32 s0, s0, s7
	v_lshl_add_u64 v[214:215], v[210:211], 0, s[42:43]
	s_mov_b32 m0, s0
	s_nop 0
	global_load_lds_dwordx4 v[214:215], off
	v_lshl_add_u64 v[214:215], v[210:211], 0, s[44:45]
	s_add_i32 m0, s0, 0x2000
	s_nop 0
	global_load_lds_dwordx4 v[214:215], off
	s_add_i32 s0, s1, s7
	v_lshl_add_u64 v[250:251], v[210:211], 0, s[46:47]
	s_mov_b32 m0, s0
	s_nop 0
	global_load_lds_dwordx4 v[250:251], off
	v_lshl_add_u64 v[250:251], v[210:211], 0, s[48:49]
	s_add_i32 m0, s0, 0x2000
	s_nop 0
	global_load_lds_dwordx4 v[250:251], off
	s_mov_b32 m0, s72
	v_lshl_add_u64 v[214:215], v[212:213], 0, s[42:43]
	global_load_lds_dwordx4 v[214:215], off
	v_lshl_add_u64 v[212:213], v[212:213], 0, s[44:45]
	s_mov_b32 m0, s73
	s_nop 0
	global_load_lds_dwordx4 v[212:213], off
	s_waitcnt vmcnt(8)
	s_waitcnt lgkmcnt(0)
	s_barrier
	s_setprio 1
	v_mfma_f32_16x16x32_bf16 v[94:97], v[130:133], v[162:165], v[94:97]
	v_mfma_f32_16x16x32_bf16 v[90:93], v[148:151], v[162:165], v[90:93]
	v_mfma_f32_16x16x32_bf16 v[86:89], v[130:133], v[170:173], v[86:89]
	v_mfma_f32_16x16x32_bf16 v[82:85], v[148:151], v[170:173], v[82:85]
	v_mfma_f32_16x16x32_bf16 v[78:81], v[130:133], v[178:181], v[78:81]
	v_mfma_f32_16x16x32_bf16 v[74:77], v[148:151], v[178:181], v[74:77]
	v_mfma_f32_16x16x32_bf16 v[70:73], v[130:133], v[186:189], v[70:73]
	v_mfma_f32_16x16x32_bf16 v[66:69], v[148:151], v[186:189], v[66:69]
	v_mfma_f32_16x16x32_bf16 v[94:97], v[134:137], v[166:169], v[94:97]
	v_mfma_f32_16x16x32_bf16 v[90:93], v[158:161], v[166:169], v[90:93]
	v_mfma_f32_16x16x32_bf16 v[86:89], v[134:137], v[174:177], v[86:89]
	v_mfma_f32_16x16x32_bf16 v[82:85], v[158:161], v[174:177], v[82:85]
	v_mfma_f32_16x16x32_bf16 v[78:81], v[134:137], v[182:185], v[78:81]
	v_mfma_f32_16x16x32_bf16 v[74:77], v[158:161], v[182:185], v[74:77]
	v_mfma_f32_16x16x32_bf16 v[70:73], v[134:137], v[190:193], v[70:73]
	v_mfma_f32_16x16x32_bf16 v[66:69], v[158:161], v[190:193], v[66:69]
	v_mfma_f32_16x16x32_bf16 v[30:33], v[194:197], v[162:165], v[30:33]
	v_mfma_f32_16x16x32_bf16 v[26:29], v[202:205], v[162:165], v[26:29]
	v_mfma_f32_16x16x32_bf16 v[22:25], v[194:197], v[170:173], v[22:25]
	v_mfma_f32_16x16x32_bf16 v[18:21], v[202:205], v[170:173], v[18:21]
	v_mfma_f32_16x16x32_bf16 v[14:17], v[194:197], v[178:181], v[14:17]
	v_mfma_f32_16x16x32_bf16 v[10:13], v[202:205], v[178:181], v[10:13]
	v_mfma_f32_16x16x32_bf16 v[6:9], v[194:197], v[186:189], v[6:9]
	v_mfma_f32_16x16x32_bf16 v[2:5], v[202:205], v[186:189], v[2:5]
	v_mfma_f32_16x16x32_bf16 v[30:33], v[198:201], v[166:169], v[30:33]
	v_mfma_f32_16x16x32_bf16 v[26:29], v[206:209], v[166:169], v[26:29]
	v_mfma_f32_16x16x32_bf16 v[22:25], v[198:201], v[174:177], v[22:25]
	v_mfma_f32_16x16x32_bf16 v[18:21], v[206:209], v[174:177], v[18:21]
	v_mfma_f32_16x16x32_bf16 v[14:17], v[198:201], v[182:185], v[14:17]
	v_mfma_f32_16x16x32_bf16 v[10:13], v[206:209], v[182:185], v[10:13]
	v_mfma_f32_16x16x32_bf16 v[6:9], v[198:201], v[190:193], v[6:9]
	v_mfma_f32_16x16x32_bf16 v[2:5], v[206:209], v[190:193], v[2:5]
	s_setprio 0
	s_add_i32 s69, s69, 2
	s_add_u32 s38, s38, 0x100
	s_addc_u32 s68, s68, 0
	s_add_u32 s66, s66, 0x100
	s_addc_u32 s67, s67, 0
	s_cmp_gt_u32 s69, 13
	s_barrier
	s_cbranch_scc0 .LBB0_1049
	s_mov_b32 s98, 1
	s_and_b64 vcc, exec, s[50:51]
	s_cbranch_vccz .LBB0_1052
	s_barrier
